# v055 + MERGE odd-workgroup start offset 6.0 us
# baseline (speedup 1.0000x reference)
.LBB0_1053:
	s_waitcnt lgkmcnt(0)
	s_barrier
	v_mbcnt_lo_u32_b32 v0, -1, 0
	v_mbcnt_hi_u32_b32 v0, -1, v0
	v_readlane_b32 s42, v255, 11
	s_mov_b32 s2, s55
	v_readlane_b32 s48, v255, 12
	s_mov_b32 s43, s84
	v_readlane_b32 s4, v255, 4
	v_readlane_b32 s6, v255, 6
	v_readlane_b32 s7, v255, 7
	s_and_b32 s41, s43, 1
	s_mov_b32 s10, s6
	s_mov_b32 s11, s7
	s_cmp_eq_u32 s41, 0
	v_readlane_b32 s5, v255, 5
	s_cbranch_scc1 .LBB0_1056
	s_memrealtime s[4:5]
	s_memrealtime s[0:1]
	v_mov_b64_e32 v[2:3], 0x257
	s_waitcnt lgkmcnt(0)
	s_sub_u32 s0, s0, s4
	s_subb_u32 s1, s1, s5
	v_cmp_gt_u64_e32 vcc, s[0:1], v[2:3]
	s_cbranch_vccnz .LBB0_1056
.LBB0_1055:
	s_sleep 8
	s_memrealtime s[0:1]
	v_mov_b64_e32 v[2:3], 0x258
	s_waitcnt lgkmcnt(0)
	s_sub_u32 s0, s0, s4
	s_subb_u32 s1, s1, s5
	v_cmp_lt_u64_e32 vcc, s[0:1], v[2:3]
	s_cbranch_vccnz .LBB0_1055
